# adds: second-level workgroup stagger (blockIdx bit 1 delays its in-projection tile loop by ~7us) to spread epilogue store bursts
# baseline (speedup 1.0000x reference)
.LBB0_236:
	v_readlane_b32 s0, v244, 16
	v_mov_b32_e32 v10, v175
	v_readlane_b32 s1, v244, 17
	s_andn2_b64 vcc, exec, s[0:1]
	v_readfirstlane_b32 s8, v10
	s_cbranch_vccnz .LBB0_252
	s_bitcmp1_b32 s2, 1
	s_cbranch_scc0 .Lstag_in
	s_sleep 127
	s_sleep 127
.Lstag_in:
	v_lshlrev_b32_e32 v0, 4, v10
	v_add_u32_e32 v1, 0x2000, v0
	v_ashrrev_i32_e32 v2, 31, v1
	v_lshrrev_b32_e32 v2, 22, v2
	v_add_u32_e32 v2, v1, v2
	v_ashrrev_i32_e32 v4, 10, v2
	v_mul_i32_i24_e32 v2, 0x400, v4
	v_sub_u32_e32 v1, v1, v2
	v_lshrrev_b32_e32 v2, 4, v1
	v_bitop3_b32 v1, v2, v1, 32 bitop3:0x6c
	v_ashrrev_i32_e32 v2, 31, v1
	v_lshrrev_b32_e32 v2, 26, v2
	v_add_u32_e32 v2, v1, v2
	v_lshlrev_b32_e32 v3, 3, v4
	s_ashr_i32 s6, s8, 6
	v_ashrrev_i32_e32 v5, 6, v2
	v_and_b32_e32 v3, -16, v3
	s_ashr_i32 s7, s8, 8
	s_lshl_b32 s87, s6, 10
	v_readlane_b32 s0, v244, 2
	v_add_u32_e32 v3, v5, v3
	s_add_u32 s91, s0, s29
	v_and_b32_e32 v6, 3, v5
	s_mov_b32 s0, 0xfffe0
	v_lshrrev_b32_e32 v7, 2, v3
	v_lshlrev_b32_e32 v8, 1, v3
	v_and_b32_e32 v2, 0xc0, v2
	v_and_or_b32 v6, v3, s0, v6
	v_and_b32_e32 v7, 4, v7
	v_and_b32_e32 v8, 24, v8
	v_sub_u32_e32 v1, v1, v2
	v_or3_b32 v7, v6, v7, v8
	v_lshlrev_b32_e32 v6, 5, v4
	v_ashrrev_i16_sdwa v1, v178, sext(v1) dst_sel:DWORD dst_unused:UNUSED_PAD src0_sel:DWORD src1_sel:BYTE_0
	v_and_b32_e32 v8, 32, v6
	v_bfe_i32 v6, v1, 0, 16
	v_add_lshl_u32 v1, v8, v6, 1
	v_lshl_add_u32 v156, v7, 12, v1
	v_lshl_add_u32 v158, v3, 12, v1
	v_bfe_i32 v1, v10, 27, 1
	v_lshrrev_b32_e32 v1, 22, v1
	v_add_u32_e32 v1, v0, v1
	v_and_b32_e32 v1, 0xfffffc00, v1
	v_sub_u32_e32 v0, v0, v1
	v_lshrrev_b32_e32 v1, 4, v0
	v_ashrrev_i32_e32 v2, 31, v10
	v_bitop3_b32 v0, v1, v0, 32 bitop3:0x6c
	v_lshrrev_b32_e32 v2, 26, v2
	v_ashrrev_i32_e32 v1, 31, v0
	v_add_u32_e32 v2, v10, v2
	v_lshrrev_b32_e32 v1, 26, v1
	v_ashrrev_i32_e32 v8, 6, v2
	v_add_u32_e32 v1, v0, v1
	v_lshlrev_b32_e32 v2, 3, v8
	v_ashrrev_i32_e32 v7, 6, v1
	v_and_b32_e32 v2, -16, v2
	v_add_u32_e32 v2, v7, v2
	v_and_b32_e32 v3, 3, v7
	v_lshrrev_b32_e32 v9, 2, v2
	v_lshlrev_b32_e32 v11, 1, v2
	v_and_b32_e32 v1, 0xc0, v1
	v_readlane_b32 s1, v244, 3
	v_and_or_b32 v3, v2, s0, v3
	v_and_b32_e32 v9, 4, v9
	v_and_b32_e32 v11, 24, v11
	v_sub_u32_e32 v0, v0, v1
	s_addc_u32 s97, s1, 0
	v_or3_b32 v3, v3, v9, v11
	v_lshlrev_b32_e32 v9, 5, v8
	v_ashrrev_i16_sdwa v0, v178, sext(v0) dst_sel:DWORD dst_unused:UNUSED_PAD src0_sel:DWORD src1_sel:BYTE_0
	v_readlane_b32 s0, v243, 33
	v_and_b32_e32 v11, 32, v9
	v_bfe_i32 v9, v0, 0, 16
	v_readlane_b32 s1, v243, 34
	s_add_u32 s72, s91, s0
	v_add_lshl_u32 v0, v11, v9, 1
	s_addc_u32 s73, s97, s1
	s_add_i32 s82, s87, 0
	v_lshl_add_u32 v144, v3, 12, v0
	s_add_i32 m0, s82, 0x10000
	v_lshl_add_u32 v160, v2, 12, v0
	global_load_lds_dwordx4 v144, s[72:73]
	s_add_i32 m0, s82, 0x12000
	s_add_u32 s0, s72, 0x80000
	global_load_lds_dwordx4 v156, s[72:73]
	s_addc_u32 s1, s73, 0
	s_add_i32 m0, s82, 0x14000
	s_add_i32 s83, s82, 0x2000
	global_load_lds_dwordx4 v144, s[0:1]
	s_add_i32 m0, s82, 0x16000
	s_add_i32 s4, s82, 0x4000
	global_load_lds_dwordx4 v156, s[0:1]
	v_readlane_b32 s0, v243, 39
	s_mov_b32 m0, s82
	v_readlane_b32 s1, v243, 40
	s_add_i32 s5, s82, 0x6000
	v_mov_b32_e32 v157, v145
	s_cmp_eq_u32 s7, 1
	v_writelane_b32 v242, s10, 48
	v_lshl_add_u64 v[0:1], s[72:73], 0, v[144:145]
	global_load_lds_dwordx4 v160, s[0:1]
	s_mov_b32 m0, s83
	v_lshl_add_u64 v[2:3], s[72:73], 0, v[156:157]
	global_load_lds_dwordx4 v158, s[0:1]
	v_readlane_b32 s0, v243, 41
	s_mov_b32 m0, s4
	v_readlane_b32 s1, v243, 42
	v_writelane_b32 v242, s11, 49
	s_nop 3
	global_load_lds_dwordx4 v160, s[0:1]
	s_mov_b32 m0, s5
	s_nop 0
	global_load_lds_dwordx4 v158, s[0:1]
	s_cselect_b64 s[0:1], -1, 0
	s_cmp_lg_u32 s7, 1
	s_cbranch_scc1 .LBB0_239
	s_barrier
